# P5 sixth round as 256 half tiles (128 rows each) so no workgroup idles; on the saddr + attention LDS-DMA version
# baseline (speedup 1.0000x reference)
;     __host__ __device__ bool next(int i, Unit& u) const { const int L = i == 0 ? l0 : (i == 1 ? l1 : (i == 2 ? l2 : -1)); if (L < 0 || L >= s.nwg) return false; return s.unit_of(L, u); }
;     __host__ __device__ bool next(int i, Unit& u) const { const bool ok = s.next(i >> 1, u); u.kh = i & 1; return ok; }
;     __host__ __device__ bool next(int i, Unit& u) const { const long L = (long)i * G + c; if (L >= nwg) return false; return unit_of((int)L, u); }
; template <class Epi, class Sched, bool ALIGN_EPI = false, bool SP2 = false>
; __device__ __forceinline__ void gemm_phase(PG8_LAS unsigned char* lds, const Gemm g, const Sched& S, const Epi& E) {
;     ...
;         for (int a = 0; a < 2; ++a)
; #pragma unroll
;             for (int b = 0; b < 2; ++b)
; #pragma unroll
;                 for (int m = 0; m < 4; ++m)
; #pragma unroll
;                     for (int n = 0; n < 2; ++n) acc[a][b][m][n] = (f32x4){0.f, 0.f, 0.f, 0.f};
.LBB0_966:
	s_add_i32 s50, s50, 1
	s_mul_i32 s2, s50, s45
	s_mul_hi_u32 s3, s50, s46
	s_add_i32 s3, s3, s2
	s_mul_i32 s2, s50, s46
	s_add_u32 s18, s2, s33
	s_addc_u32 s19, s3, s37
	s_cmp_lg_u32 s50, 5
	s_cbranch_scc1 .Lp5_sched
	s_lshr_b32 s18, s33, 4
	s_lshl_b32 s18, s18, 3
	s_and_b32 s19, s33, 7
	s_add_i32 s18, s18, s19
	s_addk_i32 s18, 0x500
	s_mov_b32 s19, 0
.Lp5_sched:
	v_cmp_gt_i64_e32 vcc, s[18:19], v[170:171]
	v_cmp_lt_i64_e64 s[2:3], s[18:19], v[168:169]
	s_cbranch_vccnz .LBB0_968
	s_ashr_i32 s14, s18, 31
	s_lshr_b32 s14, s14, 29
	s_add_i32 s14, s18, s14
	s_ashr_i32 s15, s14, 3
	s_and_b32 s14, s14, -8
	s_sub_i32 s14, s18, s14
	s_cmp_lt_i32 s14, 0
	s_cselect_b32 s16, s38, 0xb0
	s_mul_i32 s14, s14, s16
	s_add_i32 s14, s14, s15
	s_mul_hi_i32 s15, s14, 0x2e8ba2e9
	s_lshr_b32 s16, s15, 31
	s_ashr_i32 s15, s15, 5
	s_add_i32 s15, s15, s16
	s_lshl_b32 s16, s15, 3
	s_sub_i32 s17, 64, s16
	s_min_i32 s17, s17, 8
	s_abs_i32 s18, s17
	v_cvt_f32_u32_e32 v0, s18
	s_sub_i32 s20, 0, s18
	s_mulk_i32 s15, 0xb0
	s_sub_i32 s15, s14, s15
	v_rcp_iflag_f32_e32 v0, v0
	s_abs_i32 s14, s15
	s_xor_b32 s19, s15, s17
	s_ashr_i32 s19, s19, 31
	v_mul_f32_e32 v0, 0x4f7ffffe, v0
	v_cvt_u32_f32_e32 v0, v0
	s_nop 0
	v_readfirstlane_b32 s21, v0
	s_mul_i32 s20, s20, s21
	s_mul_hi_u32 s20, s21, s20
	s_add_i32 s21, s21, s20
	s_mul_hi_u32 s20, s14, s21
	s_mul_i32 s21, s20, s18
	s_sub_i32 s14, s14, s21
	s_add_i32 s28, s20, 1
	s_sub_i32 s21, s14, s18
	s_cmp_ge_u32 s14, s18
	s_cselect_b32 s20, s28, s20
	s_cselect_b32 s14, s21, s14
	s_add_i32 s21, s20, 1
	s_cmp_ge_u32 s14, s18
	s_cselect_b32 s14, s21, s20
	s_xor_b32 s14, s14, s19
	s_sub_i32 s14, s14, s19
	s_mul_i32 s17, s14, s17
	s_sub_i32 s15, s15, s17
	s_add_i32 s16, s16, s15
.LBB0_968:
	s_ashr_i32 s17, s16, 31
	s_lshl_b64 s[18:19], s[16:17], 19
	s_add_u32 s18, s30, s18
	s_addc_u32 s19, s31, s19
	s_cmp_lg_u32 s50, 5
	s_cbranch_scc1 .Lp5_ptr
	s_bfe_u32 s101, s33, 0x10003
	s_lshl_b32 s101, s101, 18
	s_add_u32 s18, s18, s101
	s_addc_u32 s19, s19, 0
.Lp5_ptr:
	s_and_b64 s[20:21], s[2:3], exec
	s_cselect_b32 s17, s19, s25
	s_cselect_b32 s51, s18, s24
	s_ashr_i32 s15, s14, 31
	s_lshl_b64 s[20:21], s[14:15], 19
	s_add_u32 s20, s34, s20
	s_addc_u32 s21, s35, s21
	s_and_b64 s[28:29], s[2:3], exec
	s_cselect_b32 s15, s21, s27
	s_cselect_b32 s54, s20, s26
	s_add_u32 s24, s24, 0x40080
	s_addc_u32 s25, s25, 0
	s_add_u32 s55, s26, 0x100
	v_mov_b32_e32 v0, 0
	s_addc_u32 s56, s27, 0
	s_mov_b32 s57, -2
	v_mov_b32_e32 v1, v0
	v_mov_b32_e32 v2, v0
	v_mov_b32_e32 v3, v0
	v_mov_b32_e32 v4, v0
	v_mov_b32_e32 v5, v0
	v_mov_b32_e32 v6, v0
	v_mov_b32_e32 v7, v0
	v_mov_b32_e32 v16, v0
	v_mov_b32_e32 v17, v0
	v_mov_b32_e32 v18, v0
	v_mov_b32_e32 v19, v0
	v_mov_b32_e32 v24, v0
	v_mov_b32_e32 v25, v0
	v_mov_b32_e32 v26, v0
	v_mov_b32_e32 v27, v0
	v_mov_b32_e32 v32, v0
	v_mov_b32_e32 v33, v0
	v_mov_b32_e32 v34, v0
	v_mov_b32_e32 v35, v0
	v_mov_b32_e32 v36, v0
	v_mov_b32_e32 v37, v0
	v_mov_b32_e32 v38, v0
	v_mov_b32_e32 v39, v0
	v_mov_b32_e32 v48, v0
	v_mov_b32_e32 v49, v0
	v_mov_b32_e32 v50, v0
	v_mov_b32_e32 v51, v0
	v_mov_b32_e32 v56, v0
	v_mov_b32_e32 v57, v0
	v_mov_b32_e32 v58, v0
	v_mov_b32_e32 v59, v0
	v_mov_b32_e32 v8, v0
	v_mov_b32_e32 v9, v0
	v_mov_b32_e32 v10, v0
	v_mov_b32_e32 v11, v0
	v_mov_b32_e32 v12, v0
	v_mov_b32_e32 v13, v0
	v_mov_b32_e32 v14, v0
	v_mov_b32_e32 v15, v0
	v_mov_b32_e32 v20, v0
	v_mov_b32_e32 v21, v0
	v_mov_b32_e32 v22, v0
	v_mov_b32_e32 v23, v0
	v_mov_b32_e32 v28, v0
	v_mov_b32_e32 v29, v0
	v_mov_b32_e32 v30, v0
	v_mov_b32_e32 v31, v0
	v_mov_b32_e32 v40, v0
	v_mov_b32_e32 v41, v0
	v_mov_b32_e32 v42, v0
	v_mov_b32_e32 v43, v0
	v_mov_b32_e32 v44, v0
	v_mov_b32_e32 v45, v0
	v_mov_b32_e32 v46, v0
	v_mov_b32_e32 v47, v0
	v_mov_b32_e32 v52, v0
	v_mov_b32_e32 v53, v0
	v_mov_b32_e32 v54, v0
	v_mov_b32_e32 v55, v0
	v_mov_b32_e32 v60, v0
	v_mov_b32_e32 v61, v0
	v_mov_b32_e32 v62, v0
	v_mov_b32_e32 v63, v0
	v_mov_b32_e32 v64, v0
	v_mov_b32_e32 v65, v0
	v_mov_b32_e32 v66, v0
	v_mov_b32_e32 v67, v0
	v_mov_b32_e32 v68, v0
	v_mov_b32_e32 v69, v0
	v_mov_b32_e32 v70, v0
	v_mov_b32_e32 v71, v0
	v_mov_b32_e32 v80, v0
	v_mov_b32_e32 v81, v0
	v_mov_b32_e32 v82, v0
	v_mov_b32_e32 v83, v0
	v_mov_b32_e32 v88, v0
	v_mov_b32_e32 v89, v0
	v_mov_b32_e32 v90, v0
	v_mov_b32_e32 v91, v0
	v_mov_b32_e32 v96, v0
	v_mov_b32_e32 v97, v0
	v_mov_b32_e32 v98, v0
	v_mov_b32_e32 v99, v0
	v_mov_b32_e32 v100, v0
	v_mov_b32_e32 v101, v0
	v_mov_b32_e32 v102, v0
	v_mov_b32_e32 v103, v0
	v_mov_b32_e32 v112, v0
	v_mov_b32_e32 v113, v0
	v_mov_b32_e32 v114, v0
	v_mov_b32_e32 v115, v0
	v_mov_b32_e32 v116, v0
	v_mov_b32_e32 v117, v0
	v_mov_b32_e32 v118, v0
	v_mov_b32_e32 v119, v0
	v_mov_b32_e32 v72, v0
	v_mov_b32_e32 v73, v0
	v_mov_b32_e32 v74, v0
	v_mov_b32_e32 v75, v0
	v_mov_b32_e32 v76, v0
	v_mov_b32_e32 v77, v0
	v_mov_b32_e32 v78, v0
	v_mov_b32_e32 v79, v0
	v_mov_b32_e32 v84, v0
	v_mov_b32_e32 v85, v0
	v_mov_b32_e32 v86, v0
	v_mov_b32_e32 v87, v0
	v_mov_b32_e32 v92, v0
	v_mov_b32_e32 v93, v0
	v_mov_b32_e32 v94, v0
	v_mov_b32_e32 v95, v0
	v_mov_b32_e32 v104, v0
	v_mov_b32_e32 v105, v0
	v_mov_b32_e32 v106, v0
	v_mov_b32_e32 v107, v0
	v_mov_b32_e32 v108, v0
	v_mov_b32_e32 v109, v0
	v_mov_b32_e32 v110, v0
	v_mov_b32_e32 v111, v0
	v_mov_b32_e32 v120, v0
	v_mov_b32_e32 v121, v0
	v_mov_b32_e32 v122, v0
	v_mov_b32_e32 v123, v0
	v_mov_b32_e32 v124, v0
	v_mov_b32_e32 v125, v0
	v_mov_b32_e32 v126, v0
	v_mov_b32_e32 v127, v0
; #define PG8_STAGE(bufoff, gbase, voff) do { _Pragma("unroll") for (int _i = 0; _i < 2; ++_i) \
;         __builtin_amdgcn_global_load_lds((const unsigned*)((const char*)(gbase) + (voff)[_i]), (PG8_LAS unsigned*)(lds + (bufoff) + ldsw + _i * 8192), 16, 0, 0); } while (0)
; #define PG8_LDA(dst, b, h) do { _Pragma("unroll") for (int m = 0; m < 4; ++m) _Pragma("unroll") for (int k = 0; k < 2; ++k) dst[m][k] = *(const PG8_LAS bf16x8*)(lds + PG8_SA(b, h) + aoff + m * 2048 + k * 1024); } while (0)
; #define PG8_LDB(dst, b, h) do { _Pragma("unroll") for (int n = 0; n < 2; ++n) _Pragma("unroll") for (int k = 0; k < 2; ++k) dst[n][k] = *(const PG8_LAS bf16x8*)(lds + PG8_SB(b, h) + boff + n * 2048 + k * 1024); } while (0)
; #define PG8_MMA(ai, bj, At, Bt) do { __builtin_amdgcn_s_setprio(1); _Pragma("unroll") for (int m = 0; m < 4; ++m) _Pragma("unroll") for (int n = 0; n < 2; ++n) _Pragma("unroll") for (int k = 0; k < 2; ++k) \
;         acc[ai][bj][m][n] = __builtin_amdgcn_mfma_f32_16x16x32_bf16(Bt[n][k], At[m][k], acc[ai][bj][m][n], 0, 0, 0); __builtin_amdgcn_s_setprio(0); } while (0)
; #define PG8_WAIT_V(n) asm volatile("s_waitcnt vmcnt(" #n ")" ::: "memory")
; #define PG8_WAIT_L(n) asm volatile("s_waitcnt lgkmcnt(" #n ")" ::: "memory")
; #define PG8_BAR __builtin_amdgcn_s_barrier()
; #define PG8_SCHED __builtin_amdgcn_sched_barrier(0)
; template <class Epi, class Sched, bool ALIGN_EPI = false, bool SP2 = false>
; __device__ __forceinline__ void gemm_phase(PG8_LAS unsigned char* lds, const Gemm g, const Sched& S, const Epi& E) {
;     ...
;             PG8_LDB(B0, 0, 0); PG8_LDB(B1, 0, 1); PG8_SCHED; PG8_LDA(At, 0, 0); PG8_STAGE(PG8_SA(1, 1), a1 + hstep, voffA);
;             PG8_WAIT_V(8); PG8_WAIT_L(0); PG8_BAR; PG8_MMA(0, 0, At, B0); PG8_MMA(0, 1, At, B1); PG8_BAR; PG8_SCHED;
;             PG8_LDA(At, 0, 1); PG8_STAGE(PG8_SB(0, 0), b2, voffB); PG8_STAGE(PG8_SB(0, 1), b2 + hstep, voffB); PG8_STAGE(PG8_SA(0, 0), a2, voffA);
;             PG8_WAIT_V(8); PG8_WAIT_L(0); PG8_BAR; PG8_MMA(1, 0, At, B0); PG8_MMA(1, 1, At, B1); PG8_BAR; PG8_SCHED;
;             PG8_LDB(B0, 1, 0); PG8_LDB(B1, 1, 1); PG8_SCHED; PG8_LDA(At, 1, 0); PG8_STAGE(PG8_SA(0, 1), a2 + hstep, voffA);
;             PG8_WAIT_V(8); PG8_WAIT_L(0); PG8_BAR; PG8_MMA(0, 0, At, B0); PG8_MMA(0, 1, At, B1); PG8_BAR; PG8_SCHED;
.LBB0_969:
	ds_read_b128 v[128:131], v191
	ds_read_b128 v[132:135], v191 offset:1024
	ds_read_b128 v[136:139], v191 offset:2048
	ds_read_b128 v[140:143], v191 offset:3072
	ds_read_b128 v[144:147], v192
	ds_read_b128 v[148:151], v192 offset:1024
	ds_read_b128 v[172:175], v192 offset:2048
	ds_read_b128 v[176:179], v192 offset:3072
	s_add_u32 s26, s24, 0xfffc0080
	s_addc_u32 s27, s25, -1
	s_cmp_eq_u32 s57, 12
	s_cselect_b32 s29, s17, s27
	s_cselect_b32 s28, s51, s26
	s_cselect_b32 s27, s15, s56
	s_cselect_b32 s26, s54, s55
	s_add_i32 m0, s39, 0xc000
	ds_read_b128 v[180:183], v193
	ds_read_b128 v[184:187], v193 offset:1024
	ds_read_b128 v[196:199], v193 offset:2048
	ds_read_b128 v[200:203], v193 offset:3072
	ds_read_b128 v[204:207], v193 offset:4096
	ds_read_b128 v[208:211], v193 offset:5120
	ds_read_b128 v[212:215], v193 offset:6144
	ds_read_b128 v[216:219], v193 offset:7168
	global_load_lds_dwordx4 v164, s[24:25]
	s_add_i32 m0, s39, 0xe000
	s_nop 0
	global_load_lds_dwordx4 v166, s[24:25]
	s_waitcnt vmcnt(8)
	s_waitcnt lgkmcnt(0)
	s_barrier
	s_setprio 1
	s_waitcnt lgkmcnt(0)
	v_mfma_f32_16x16x32_bf16 v[124:127], v[128:131], v[180:183], v[124:127]
	v_mfma_f32_16x16x32_bf16 v[120:123], v[136:139], v[180:183], v[120:123]
	v_mfma_f32_16x16x32_bf16 v[108:111], v[128:131], v[196:199], v[108:111]
	v_mfma_f32_16x16x32_bf16 v[104:107], v[136:139], v[196:199], v[104:107]
	v_mfma_f32_16x16x32_bf16 v[92:95], v[128:131], v[204:207], v[92:95]
	v_mfma_f32_16x16x32_bf16 v[84:87], v[136:139], v[204:207], v[84:87]
	v_mfma_f32_16x16x32_bf16 v[76:79], v[128:131], v[212:215], v[76:79]
	v_mfma_f32_16x16x32_bf16 v[72:75], v[136:139], v[212:215], v[72:75]
	v_mfma_f32_16x16x32_bf16 v[124:127], v[132:135], v[184:187], v[124:127]
	v_mfma_f32_16x16x32_bf16 v[120:123], v[140:143], v[184:187], v[120:123]
	v_mfma_f32_16x16x32_bf16 v[108:111], v[132:135], v[200:203], v[108:111]
	v_mfma_f32_16x16x32_bf16 v[104:107], v[140:143], v[200:203], v[104:107]
	v_mfma_f32_16x16x32_bf16 v[92:95], v[132:135], v[208:211], v[92:95]
	v_mfma_f32_16x16x32_bf16 v[84:87], v[140:143], v[208:211], v[84:87]
	v_mfma_f32_16x16x32_bf16 v[76:79], v[132:135], v[216:219], v[76:79]
	v_mfma_f32_16x16x32_bf16 v[72:75], v[140:143], v[216:219], v[72:75]
	s_setprio 0
	s_setprio 1
	v_mfma_f32_16x16x32_bf16 v[116:119], v[144:147], v[180:183], v[116:119]
	v_mfma_f32_16x16x32_bf16 v[112:115], v[172:175], v[180:183], v[112:115]
	v_mfma_f32_16x16x32_bf16 v[100:103], v[144:147], v[196:199], v[100:103]
	v_mfma_f32_16x16x32_bf16 v[96:99], v[172:175], v[196:199], v[96:99]
	v_mfma_f32_16x16x32_bf16 v[88:91], v[144:147], v[204:207], v[88:91]
	v_mfma_f32_16x16x32_bf16 v[80:83], v[172:175], v[204:207], v[80:83]
	v_mfma_f32_16x16x32_bf16 v[68:71], v[144:147], v[212:215], v[68:71]
	v_mfma_f32_16x16x32_bf16 v[64:67], v[172:175], v[212:215], v[64:67]
	v_mfma_f32_16x16x32_bf16 v[116:119], v[148:151], v[184:187], v[116:119]
	v_mfma_f32_16x16x32_bf16 v[112:115], v[176:179], v[184:187], v[112:115]
	v_mfma_f32_16x16x32_bf16 v[100:103], v[148:151], v[200:203], v[100:103]
	v_mfma_f32_16x16x32_bf16 v[96:99], v[176:179], v[200:203], v[96:99]
	v_mfma_f32_16x16x32_bf16 v[88:91], v[148:151], v[208:211], v[88:91]
	v_mfma_f32_16x16x32_bf16 v[80:83], v[176:179], v[208:211], v[80:83]
	v_mfma_f32_16x16x32_bf16 v[68:71], v[148:151], v[216:219], v[68:71]
	v_mfma_f32_16x16x32_bf16 v[64:67], v[176:179], v[216:219], v[64:67]
	s_setprio 0
	s_barrier
	s_add_i32 s58, s47, s36
	v_lshl_add_u64 v[220:221], s[26:27], 0, v[156:157]
	s_mov_b32 m0, s58
	ds_read_b128 v[180:183], v193 offset:16384
	ds_read_b128 v[184:187], v193 offset:17408
	ds_read_b128 v[196:199], v193 offset:18432
	ds_read_b128 v[200:203], v193 offset:19456
	ds_read_b128 v[204:207], v193 offset:20480
	ds_read_b128 v[208:211], v193 offset:21504
	ds_read_b128 v[212:215], v193 offset:22528
	ds_read_b128 v[216:219], v193 offset:23552
	global_load_lds_dwordx4 v[220:221], off
	s_add_i32 m0, s58, 0x2000
	s_add_u32 s58, s26, 0x40000
	v_lshl_add_u64 v[222:223], s[26:27], 0, v[152:153]
	s_addc_u32 s59, s27, 0
	s_add_i32 s60, s48, s36
	global_load_lds_dwordx4 v[222:223], off
	s_mov_b32 m0, s60
	v_lshl_add_u64 v[226:227], s[28:29], 0, v[154:155]
	global_load_lds_dwordx4 v156, s[58:59]
	s_add_i32 m0, s60, 0x2000
	s_nop 0
	global_load_lds_dwordx4 v152, s[58:59]
	v_lshl_add_u64 v[224:225], s[28:29], 0, v[158:159]
	s_mov_b32 m0, s39
	s_nop 0
	global_load_lds_dwordx4 v[224:225], off
	s_mov_b32 m0, s40
	s_nop 0
	global_load_lds_dwordx4 v[226:227], off
	s_waitcnt vmcnt(8)
	s_waitcnt lgkmcnt(0)
	s_barrier
	s_cmp_eq_u32 s50, 6
	s_cbranch_scc1 .Lp5_skip_b2
	s_setprio 1
	s_waitcnt lgkmcnt(0)
	v_mfma_f32_16x16x32_bf16 v[60:63], v[128:131], v[180:183], v[60:63]
	v_mfma_f32_16x16x32_bf16 v[52:55], v[136:139], v[180:183], v[52:55]
	v_mfma_f32_16x16x32_bf16 v[44:47], v[128:131], v[196:199], v[44:47]
	v_mfma_f32_16x16x32_bf16 v[40:43], v[136:139], v[196:199], v[40:43]
	v_mfma_f32_16x16x32_bf16 v[28:31], v[128:131], v[204:207], v[28:31]
	v_mfma_f32_16x16x32_bf16 v[20:23], v[136:139], v[204:207], v[20:23]
	v_mfma_f32_16x16x32_bf16 v[12:15], v[128:131], v[212:215], v[12:15]
	v_mfma_f32_16x16x32_bf16 v[8:11], v[136:139], v[212:215], v[8:11]
	v_mfma_f32_16x16x32_bf16 v[60:63], v[132:135], v[184:187], v[60:63]
	v_mfma_f32_16x16x32_bf16 v[52:55], v[140:143], v[184:187], v[52:55]
	v_mfma_f32_16x16x32_bf16 v[44:47], v[132:135], v[200:203], v[44:47]
	v_mfma_f32_16x16x32_bf16 v[40:43], v[140:143], v[200:203], v[40:43]
	v_mfma_f32_16x16x32_bf16 v[28:31], v[132:135], v[208:211], v[28:31]
	v_mfma_f32_16x16x32_bf16 v[20:23], v[140:143], v[208:211], v[20:23]
	v_mfma_f32_16x16x32_bf16 v[12:15], v[132:135], v[216:219], v[12:15]
	v_mfma_f32_16x16x32_bf16 v[8:11], v[140:143], v[216:219], v[8:11]
	s_setprio 0
	s_setprio 1
	v_mfma_f32_16x16x32_bf16 v[56:59], v[144:147], v[180:183], v[56:59]
	v_mfma_f32_16x16x32_bf16 v[48:51], v[172:175], v[180:183], v[48:51]
	v_mfma_f32_16x16x32_bf16 v[36:39], v[144:147], v[196:199], v[36:39]
	v_mfma_f32_16x16x32_bf16 v[32:35], v[172:175], v[196:199], v[32:35]
	v_mfma_f32_16x16x32_bf16 v[24:27], v[144:147], v[204:207], v[24:27]
	v_mfma_f32_16x16x32_bf16 v[16:19], v[172:175], v[204:207], v[16:19]
	v_mfma_f32_16x16x32_bf16 v[4:7], v[144:147], v[212:215], v[4:7]
	v_mfma_f32_16x16x32_bf16 v[0:3], v[172:175], v[212:215], v[0:3]
	v_mfma_f32_16x16x32_bf16 v[56:59], v[148:151], v[184:187], v[56:59]
	v_mfma_f32_16x16x32_bf16 v[48:51], v[176:179], v[184:187], v[48:51]
	v_mfma_f32_16x16x32_bf16 v[36:39], v[148:151], v[200:203], v[36:39]
	v_mfma_f32_16x16x32_bf16 v[32:35], v[176:179], v[200:203], v[32:35]
	v_mfma_f32_16x16x32_bf16 v[24:27], v[148:151], v[208:211], v[24:27]
	v_mfma_f32_16x16x32_bf16 v[16:19], v[176:179], v[208:211], v[16:19]
	v_mfma_f32_16x16x32_bf16 v[4:7], v[148:151], v[216:219], v[4:7]
	v_mfma_f32_16x16x32_bf16 v[0:3], v[176:179], v[216:219], v[0:3]
	s_setprio 0
; #define PG8_STAGE(bufoff, gbase, voff) do { _Pragma("unroll") for (int _i = 0; _i < 2; ++_i) \
;         __builtin_amdgcn_global_load_lds((const unsigned*)((const char*)(gbase) + (voff)[_i]), (PG8_LAS unsigned*)(lds + (bufoff) + ldsw + _i * 8192), 16, 0, 0); } while (0)
; #define PG8_LDA(dst, b, h) do { _Pragma("unroll") for (int m = 0; m < 4; ++m) _Pragma("unroll") for (int k = 0; k < 2; ++k) dst[m][k] = *(const PG8_LAS bf16x8*)(lds + PG8_SA(b, h) + aoff + m * 2048 + k * 1024); } while (0)
; #define PG8_LDB(dst, b, h) do { _Pragma("unroll") for (int n = 0; n < 2; ++n) _Pragma("unroll") for (int k = 0; k < 2; ++k) dst[n][k] = *(const PG8_LAS bf16x8*)(lds + PG8_SB(b, h) + boff + n * 2048 + k * 1024); } while (0)
; #define PG8_MMA(ai, bj, At, Bt) do { __builtin_amdgcn_s_setprio(1); _Pragma("unroll") for (int m = 0; m < 4; ++m) _Pragma("unroll") for (int n = 0; n < 2; ++n) _Pragma("unroll") for (int k = 0; k < 2; ++k) \
;         acc[ai][bj][m][n] = __builtin_amdgcn_mfma_f32_16x16x32_bf16(Bt[n][k], At[m][k], acc[ai][bj][m][n], 0, 0, 0); __builtin_amdgcn_s_setprio(0); } while (0)
; #define PG8_WAIT_V(n) asm volatile("s_waitcnt vmcnt(" #n ")" ::: "memory")
; #define PG8_WAIT_L(n) asm volatile("s_waitcnt lgkmcnt(" #n ")" ::: "memory")
; #define PG8_BAR __builtin_amdgcn_s_barrier()
; #define PG8_SCHED __builtin_amdgcn_sched_barrier(0)
; template <class Epi, class Sched, bool ALIGN_EPI = false, bool SP2 = false>
; __device__ __forceinline__ void gemm_phase(PG8_LAS unsigned char* lds, const Gemm g, const Sched& S, const Epi& E) {
;     ...
;             PG8_LDB(B0, 1, 0); PG8_LDB(B1, 1, 1); PG8_SCHED; PG8_LDA(At, 1, 0); PG8_STAGE(PG8_SA(0, 1), a2 + hstep, voffA);
;             PG8_WAIT_V(8); PG8_WAIT_L(0); PG8_BAR; PG8_MMA(0, 0, At, B0); PG8_MMA(0, 1, At, B1); PG8_BAR; PG8_SCHED;
;             PG8_LDA(At, 1, 1); PG8_STAGE(PG8_SB(1, 0), b3, voffB); PG8_STAGE(PG8_SB(1, 1), b3 + hstep, voffB); PG8_STAGE(PG8_SA(1, 0), a3, voffA);
;             PG8_WAIT_V(8); PG8_WAIT_L(0); PG8_BAR; PG8_MMA(1, 0, At, B0); PG8_MMA(1, 1, At, B1); PG8_BAR; PG8_SCHED;
.Lp5_skip_b2:
	s_barrier
	s_add_i32 s58, 0, 0x18000
	s_add_i32 s59, 0, 0x1c000
	v_add_u32_e32 v140, s58, v190
	v_add_u32_e32 v176, s59, v190
	ds_read_b128 v[128:131], v140
	ds_read_b128 v[132:135], v140 offset:1024
	ds_read_b128 v[136:139], v140 offset:2048
	ds_read_b128 v[140:143], v140 offset:3072
	ds_read_b128 v[144:147], v176
	ds_read_b128 v[148:151], v176 offset:1024
	ds_read_b128 v[172:175], v176 offset:2048
	ds_read_b128 v[176:179], v176 offset:3072
	s_add_u32 s28, s28, 0x40000
	s_addc_u32 s29, s29, 0
	s_mov_b32 m0, s41
	ds_read_b128 v[180:183], v193 offset:32768
	ds_read_b128 v[184:187], v193 offset:33792
	ds_read_b128 v[196:199], v193 offset:34816
	ds_read_b128 v[200:203], v193 offset:35840
	ds_read_b128 v[204:207], v193 offset:36864
	ds_read_b128 v[208:211], v193 offset:37888
	ds_read_b128 v[212:215], v193 offset:38912
	ds_read_b128 v[216:219], v193 offset:39936
	global_load_lds_dwordx4 v158, s[28:29]
	s_mov_b32 m0, s42
	s_nop 0
	global_load_lds_dwordx4 v154, s[28:29]
	s_waitcnt vmcnt(8)
	s_waitcnt lgkmcnt(0)
	s_barrier
	s_setprio 1
	s_waitcnt lgkmcnt(0)
	v_mfma_f32_16x16x32_bf16 v[124:127], v[128:131], v[180:183], v[124:127]
	v_mfma_f32_16x16x32_bf16 v[120:123], v[136:139], v[180:183], v[120:123]
	v_mfma_f32_16x16x32_bf16 v[108:111], v[128:131], v[196:199], v[108:111]
	v_mfma_f32_16x16x32_bf16 v[104:107], v[136:139], v[196:199], v[104:107]
	v_mfma_f32_16x16x32_bf16 v[92:95], v[128:131], v[204:207], v[92:95]
	v_mfma_f32_16x16x32_bf16 v[84:87], v[136:139], v[204:207], v[84:87]
	v_mfma_f32_16x16x32_bf16 v[76:79], v[128:131], v[212:215], v[76:79]
	v_mfma_f32_16x16x32_bf16 v[72:75], v[136:139], v[212:215], v[72:75]
	v_mfma_f32_16x16x32_bf16 v[124:127], v[132:135], v[184:187], v[124:127]
	v_mfma_f32_16x16x32_bf16 v[120:123], v[140:143], v[184:187], v[120:123]
	v_mfma_f32_16x16x32_bf16 v[108:111], v[132:135], v[200:203], v[108:111]
	v_mfma_f32_16x16x32_bf16 v[104:107], v[140:143], v[200:203], v[104:107]
	v_mfma_f32_16x16x32_bf16 v[92:95], v[132:135], v[208:211], v[92:95]
	v_mfma_f32_16x16x32_bf16 v[84:87], v[140:143], v[208:211], v[84:87]
	v_mfma_f32_16x16x32_bf16 v[76:79], v[132:135], v[216:219], v[76:79]
	v_mfma_f32_16x16x32_bf16 v[72:75], v[140:143], v[216:219], v[72:75]
	s_setprio 0
	s_setprio 1
	v_mfma_f32_16x16x32_bf16 v[116:119], v[144:147], v[180:183], v[116:119]
	v_mfma_f32_16x16x32_bf16 v[112:115], v[172:175], v[180:183], v[112:115]
	v_mfma_f32_16x16x32_bf16 v[100:103], v[144:147], v[196:199], v[100:103]
	v_mfma_f32_16x16x32_bf16 v[96:99], v[172:175], v[196:199], v[96:99]
	v_mfma_f32_16x16x32_bf16 v[88:91], v[144:147], v[204:207], v[88:91]
	v_mfma_f32_16x16x32_bf16 v[80:83], v[172:175], v[204:207], v[80:83]
	v_mfma_f32_16x16x32_bf16 v[68:71], v[144:147], v[212:215], v[68:71]
	v_mfma_f32_16x16x32_bf16 v[64:67], v[172:175], v[212:215], v[64:67]
	v_mfma_f32_16x16x32_bf16 v[116:119], v[148:151], v[184:187], v[116:119]
	v_mfma_f32_16x16x32_bf16 v[112:115], v[176:179], v[184:187], v[112:115]
	v_mfma_f32_16x16x32_bf16 v[100:103], v[148:151], v[200:203], v[100:103]
	v_mfma_f32_16x16x32_bf16 v[96:99], v[176:179], v[200:203], v[96:99]
	v_mfma_f32_16x16x32_bf16 v[88:91], v[148:151], v[208:211], v[88:91]
	v_mfma_f32_16x16x32_bf16 v[80:83], v[176:179], v[208:211], v[80:83]
	v_mfma_f32_16x16x32_bf16 v[68:71], v[148:151], v[216:219], v[68:71]
	v_mfma_f32_16x16x32_bf16 v[64:67], v[176:179], v[216:219], v[64:67]
	s_setprio 0
	s_barrier
	s_add_i32 s28, s58, s36
	v_lshl_add_u64 v[220:221], v[220:221], 0, s[10:11]
	s_mov_b32 m0, s28
	ds_read_b128 v[180:183], v193 offset:49152
	ds_read_b128 v[184:187], v193 offset:50176
	ds_read_b128 v[196:199], v193 offset:51200
	ds_read_b128 v[200:203], v193 offset:52224
	ds_read_b128 v[204:207], v193 offset:53248
	ds_read_b128 v[208:211], v193 offset:54272
	ds_read_b128 v[212:215], v193 offset:55296
	ds_read_b128 v[216:219], v193 offset:56320
	global_load_lds_dwordx4 v[220:221], off
	s_add_i32 m0, s28, 0x2000
	s_add_u32 s26, s26, 0x40080
	v_lshl_add_u64 v[220:221], v[222:223], 0, s[10:11]
	s_addc_u32 s27, s27, 0
	s_add_i32 s28, s59, s36
	global_load_lds_dwordx4 v[220:221], off
	s_mov_b32 m0, s28
	s_nop 0
	global_load_lds_dwordx4 v156, s[26:27]
	s_add_i32 m0, s28, 0x2000
	s_nop 0
	global_load_lds_dwordx4 v152, s[26:27]
	v_lshl_add_u64 v[220:221], v[224:225], 0, s[10:11]
	s_mov_b32 m0, s43
	s_nop 0
	global_load_lds_dwordx4 v[220:221], off
	v_lshl_add_u64 v[220:221], v[226:227], 0, s[10:11]
	s_mov_b32 m0, s44
	s_nop 0
	global_load_lds_dwordx4 v[220:221], off
	s_waitcnt vmcnt(8)
	s_waitcnt lgkmcnt(0)
	s_barrier
	s_cmp_eq_u32 s50, 6
	s_cbranch_scc1 .Lp5_skip_b4
	s_setprio 1
	s_waitcnt lgkmcnt(0)
	v_mfma_f32_16x16x32_bf16 v[60:63], v[128:131], v[180:183], v[60:63]
	v_mfma_f32_16x16x32_bf16 v[52:55], v[136:139], v[180:183], v[52:55]
	v_mfma_f32_16x16x32_bf16 v[44:47], v[128:131], v[196:199], v[44:47]
	v_mfma_f32_16x16x32_bf16 v[40:43], v[136:139], v[196:199], v[40:43]
	v_mfma_f32_16x16x32_bf16 v[28:31], v[128:131], v[204:207], v[28:31]
	v_mfma_f32_16x16x32_bf16 v[20:23], v[136:139], v[204:207], v[20:23]
	v_mfma_f32_16x16x32_bf16 v[12:15], v[128:131], v[212:215], v[12:15]
	v_mfma_f32_16x16x32_bf16 v[8:11], v[136:139], v[212:215], v[8:11]
	v_mfma_f32_16x16x32_bf16 v[60:63], v[132:135], v[184:187], v[60:63]
	v_mfma_f32_16x16x32_bf16 v[52:55], v[140:143], v[184:187], v[52:55]
	v_mfma_f32_16x16x32_bf16 v[44:47], v[132:135], v[200:203], v[44:47]
	v_mfma_f32_16x16x32_bf16 v[40:43], v[140:143], v[200:203], v[40:43]
	v_mfma_f32_16x16x32_bf16 v[28:31], v[132:135], v[208:211], v[28:31]
	v_mfma_f32_16x16x32_bf16 v[20:23], v[140:143], v[208:211], v[20:23]
	v_mfma_f32_16x16x32_bf16 v[12:15], v[132:135], v[216:219], v[12:15]
	v_mfma_f32_16x16x32_bf16 v[8:11], v[140:143], v[216:219], v[8:11]
	s_setprio 0
	s_setprio 1
	v_mfma_f32_16x16x32_bf16 v[56:59], v[144:147], v[180:183], v[56:59]
	v_mfma_f32_16x16x32_bf16 v[48:51], v[172:175], v[180:183], v[48:51]
	v_mfma_f32_16x16x32_bf16 v[36:39], v[144:147], v[196:199], v[36:39]
	v_mfma_f32_16x16x32_bf16 v[32:35], v[172:175], v[196:199], v[32:35]
	v_mfma_f32_16x16x32_bf16 v[24:27], v[144:147], v[204:207], v[24:27]
	v_mfma_f32_16x16x32_bf16 v[16:19], v[172:175], v[204:207], v[16:19]
	v_mfma_f32_16x16x32_bf16 v[4:7], v[144:147], v[212:215], v[4:7]
	v_mfma_f32_16x16x32_bf16 v[0:3], v[172:175], v[212:215], v[0:3]
	v_mfma_f32_16x16x32_bf16 v[56:59], v[148:151], v[184:187], v[56:59]
	v_mfma_f32_16x16x32_bf16 v[48:51], v[176:179], v[184:187], v[48:51]
	v_mfma_f32_16x16x32_bf16 v[36:39], v[148:151], v[200:203], v[36:39]
	v_mfma_f32_16x16x32_bf16 v[32:35], v[176:179], v[200:203], v[32:35]
	v_mfma_f32_16x16x32_bf16 v[24:27], v[148:151], v[208:211], v[24:27]
	v_mfma_f32_16x16x32_bf16 v[16:19], v[176:179], v[208:211], v[16:19]
	v_mfma_f32_16x16x32_bf16 v[4:7], v[148:151], v[216:219], v[4:7]
	v_mfma_f32_16x16x32_bf16 v[0:3], v[176:179], v[216:219], v[0:3]
	s_setprio 0
; __device__ __forceinline__ float sigm(float x) { return __builtin_amdgcn_rcpf(1.0f + __expf(-x)); }
; __device__ __forceinline__ u32x4 pack8_bf16(const float (&o)[8]) { u32x4 w; w.x = cvt_pk_bf16(o[0], o[1]); w.y = cvt_pk_bf16(o[2], o[3]); w.z = cvt_pk_bf16(o[4], o[5]); w.w = cvt_pk_bf16(o[6], o[7]); return w; }
;     __device__ __forceinline__ void operator()(const f32x4 (&acc)[2][2][4][2], const Unit& u, int wr, int wc, int fr, int fq) const {
;         const int row0 = u.pm * BM + wr * 64 + fr;
;         f32x4 sq[2][4];
; #pragma unroll
;         for (int ai = 0; ai < 2; ++ai)
; #pragma unroll
;             for (int m = 0; m < 4; ++m) sq[ai][m] = *(const f32x4*)(SSQ + (size_t)(row0 + ai * HALF + m * 16) * 16 + 4 * fq);
; #pragma unroll
;         for (int ai = 0; ai < 2; ++ai)
; #pragma unroll
;             for (int m = 0; m < 4; ++m) {
;                 const int row = row0 + ai * HALF + m * 16;
;                 float ss = (sq[ai][m][0] + sq[ai][m][1]) + (sq[ai][m][2] + sq[ai][m][3]);
;                 ss += __shfl_xor(ss, 16); ss += __shfl_xor(ss, 32);
;                 const float rstd = __builtin_amdgcn_rsqf(ss * (1.0f / 1024.0f) + 1e-6f);
;                 float o[8];
; #pragma unroll
;                 for (int k = 0; k < 8; ++k) { const float g = acc[ai][0][m][k >> 2][k & 3] * rstd, up = acc[ai][1][m][k >> 2][k & 3] * rstd; o[k] = g * sigm(g) * up; }
;                 *(u32x4*)(ACT + (size_t)row * 2816 + u.pn * 128 + wc * 32 + 8 * fq) = pack8_bf16(o);
.Lp5_skip_b4:
	s_barrier
	s_add_i32 s57, s57, 2
	s_add_u32 s24, s24, 0x100
	s_addc_u32 s25, s25, 0
	s_add_u32 s55, s55, 0x100
	s_addc_u32 s56, s56, 0
	s_cmp_gt_u32 s57, 13
	s_cbranch_scc0 .LBB0_969
	s_and_b64 vcc, exec, s[12:13]
	s_cbranch_vccz .LBB0_972
	s_barrier
.LBB0_972:
	v_lshl_add_u32 v186, s22, 8, v189
	s_cmp_lg_u32 s50, 6
	s_cbranch_scc1 .Lp5_row
	s_bfe_u32 s101, s33, 0x10003
	s_lshl_b32 s101, s101, 7
	s_nop 0
	v_add_u32_e32 v186, s101, v186
.Lp5_row:
	v_ashrrev_i32_e32 v187, 31, v186
	v_lshlrev_b64 v[128:129], 6, v[186:187]
	v_lshl_add_u64 v[128:129], v[162:163], 0, v[128:129]
	global_load_dwordx4 v[128:131], v[128:129], off
	v_or_b32_e32 v184, 16, v186
	v_ashrrev_i32_e32 v185, 31, v184
	v_lshlrev_b64 v[132:133], 6, v[184:185]
	v_lshl_add_u64 v[132:133], v[162:163], 0, v[132:133]
	global_load_dwordx4 v[196:199], v[132:133], off
	v_and_b32_e32 v133, 64, v194
	v_xor_b32_e32 v132, 16, v194
	v_or_b32_e32 v182, 32, v186
	v_add_u32_e32 v178, 0x80, v186
	v_add_u32_e32 v176, 0x90, v186
	v_add_u32_e32 v174, 0xa0, v186
	v_add_u32_e32 v133, 64, v133
	v_xor_b32_e32 v134, 32, v194
	v_or_b32_e32 v180, 48, v186
	v_add_u32_e32 v172, 0xb0, v186
	v_ashrrev_i32_e32 v183, 31, v182
	v_ashrrev_i32_e32 v179, 31, v178
	v_ashrrev_i32_e32 v177, 31, v176
	v_ashrrev_i32_e32 v175, 31, v174
	v_cmp_lt_i32_e32 vcc, v132, v133
	v_ashrrev_i32_e32 v181, 31, v180
	v_ashrrev_i32_e32 v173, 31, v172
	v_cndmask_b32_e32 v144, v194, v132, vcc
	v_cmp_lt_i32_e32 vcc, v134, v133
	v_lshlrev_b64 v[132:133], 6, v[182:183]
	v_lshlrev_b64 v[136:137], 6, v[178:179]
	v_lshlrev_b64 v[138:139], 6, v[176:177]
	v_lshlrev_b64 v[140:141], 6, v[174:175]
	v_cndmask_b32_e32 v145, v194, v134, vcc
	v_lshlrev_b64 v[134:135], 6, v[180:181]
	v_lshlrev_b64 v[142:143], 6, v[172:173]
	v_lshl_add_u64 v[132:133], v[162:163], 0, v[132:133]
	v_lshl_add_u64 v[136:137], v[162:163], 0, v[136:137]
	v_lshl_add_u64 v[138:139], v[162:163], 0, v[138:139]
	v_lshl_add_u64 v[200:201], v[162:163], 0, v[140:141]
	v_lshlrev_b32_e32 v175, 2, v144
	v_lshlrev_b32_e32 v173, 2, v145
	v_lshl_add_u64 v[134:135], v[162:163], 0, v[134:135]
	v_lshl_add_u64 v[202:203], v[162:163], 0, v[142:143]
	s_lshl_b32 s22, s23, 7
	s_ashr_i32 s23, s22, 31
	s_lshl_b64 s[22:23], s[22:23], 1
	s_andn2_b64 vcc, exec, s[2:3]
	s_mov_b64 s[2:3], -1
	s_waitcnt vmcnt(0)
	v_mov_b32_e32 v140, v129
	v_mov_b32_e32 v141, v130
	v_mov_b32_e32 v129, v131
	v_pk_add_f32 v[128:129], v[140:141], v[128:129]
	global_load_dwordx4 v[148:151], v[132:133], off
	global_load_dwordx4 v[144:147], v[134:135], off
	global_load_dwordx4 v[140:143], v[136:137], off
	s_nop 0
	global_load_dwordx4 v[136:139], v[138:139], off
	v_add_f32_e32 v128, v128, v129
	ds_bpermute_b32 v129, v175, v128
	s_waitcnt lgkmcnt(0)
	v_add_f32_e32 v177, v128, v129
	ds_bpermute_b32 v179, v173, v177
	global_load_dwordx4 v[132:135], v[200:201], off
	global_load_dwordx4 v[128:131], v[202:203], off
	v_mov_b32_e32 v201, v198
	v_mov_b32_e32 v200, v197
	v_mov_b32_e32 v197, v199
	s_waitcnt lgkmcnt(0)
	v_add_f32_e32 v177, v177, v179
	v_fmamk_f32 v177, v177, 0x3a800000, v195
	v_rsq_f32_e32 v198, v177
	v_pk_add_f32 v[196:197], v[200:201], v[196:197]
	v_pk_mul_f32 v[124:125], v[124:125], v[198:199] op_sel_hi:[1,0]
	v_pk_mul_f32 v[120:121], v[120:121], v[198:199] op_sel_hi:[1,0]
	v_pk_mul_f32 v[122:123], v[122:123], v[198:199] op_sel_hi:[1,0]
	v_add_f32_e32 v177, v196, v197
	v_pk_mul_f32 v[116:117], v[116:117], v[198:199] op_sel_hi:[1,0]
	v_pk_mul_f32 v[126:127], v[126:127], v[198:199] op_sel_hi:[1,0]
	v_pk_mul_f32 v[118:119], v[118:119], v[198:199] op_sel_hi:[1,0]
	v_pk_mul_f32 v[112:113], v[112:113], v[198:199] op_sel_hi:[1,0]
	v_pk_mul_f32 v[114:115], v[114:115], v[198:199] op_sel_hi:[1,0]
	v_mul_f32_e32 v181, 0xbfb8aa3b, v124
	v_mul_f32_e32 v183, 0xbfb8aa3b, v125
	v_mul_f32_e32 v196, 0xbfb8aa3b, v120
	v_mul_f32_e32 v197, 0xbfb8aa3b, v121
	v_mul_f32_e32 v198, 0xbfb8aa3b, v122
	v_mul_f32_e32 v199, 0xbfb8aa3b, v123
	v_exp_f32_e32 v181, v181
	v_exp_f32_e32 v183, v183
	v_exp_f32_e32 v196, v196
	v_exp_f32_e32 v197, v197
	v_exp_f32_e32 v198, v198
	v_exp_f32_e32 v199, v199
	v_add_f32_e32 v181, 1.0, v181
	v_add_f32_e32 v183, 1.0, v183
	v_add_f32_e32 v200, 1.0, v196
	v_add_f32_e32 v201, 1.0, v197
	v_add_f32_e32 v202, 1.0, v198
	v_add_f32_e32 v203, 1.0, v199
	v_rcp_f32_e32 v196, v181
	v_rcp_f32_e32 v197, v183
	v_rcp_f32_e32 v200, v200
	v_rcp_f32_e32 v201, v201
	v_rcp_f32_e32 v202, v202
	v_rcp_f32_e32 v203, v203
	ds_bpermute_b32 v179, v175, v177
	v_pk_mul_f32 v[124:125], v[124:125], v[196:197]
	v_pk_mul_f32 v[120:121], v[120:121], v[200:201]
	v_pk_mul_f32 v[122:123], v[122:123], v[202:203]
	v_pk_mul_f32 v[116:117], v[116:117], v[124:125]
	v_pk_mul_f32 v[112:113], v[112:113], v[120:121]
	v_pk_mul_f32 v[120:121], v[114:115], v[122:123]
	v_cvt_pk_bf16_f32 v114, v116, v117
	v_cvt_pk_bf16_f32 v117, v120, v121
	s_waitcnt lgkmcnt(0)
	v_add_f32_e32 v120, v177, v179
	ds_bpermute_b32 v121, v173, v120
	v_mul_f32_e32 v185, 0xbfb8aa3b, v126
	v_mul_f32_e32 v187, 0xbfb8aa3b, v127
	v_exp_f32_e32 v185, v185
	v_exp_f32_e32 v187, v187
	s_waitcnt lgkmcnt(0)
; __device__ __forceinline__ float sigm(float x) { return __builtin_amdgcn_rcpf(1.0f + __expf(-x)); }
; __device__ __forceinline__ u32x4 pack8_bf16(const float (&o)[8]) { u32x4 w; w.x = cvt_pk_bf16(o[0], o[1]); w.y = cvt_pk_bf16(o[2], o[3]); w.z = cvt_pk_bf16(o[4], o[5]); w.w = cvt_pk_bf16(o[6], o[7]); return w; }
;     __device__ __forceinline__ void operator()(const f32x4 (&acc)[2][2][4][2], const Unit& u, int wr, int wc, int fr, int fq) const {
;     ...
;         for (int ai = 0; ai < 2; ++ai)
; #pragma unroll
;             for (int m = 0; m < 4; ++m) {
;                 const int row = row0 + ai * HALF + m * 16;
;                 float ss = (sq[ai][m][0] + sq[ai][m][1]) + (sq[ai][m][2] + sq[ai][m][3]);
;                 ss += __shfl_xor(ss, 16); ss += __shfl_xor(ss, 32);
;                 const float rstd = __builtin_amdgcn_rsqf(ss * (1.0f / 1024.0f) + 1e-6f);
;                 float o[8];
; #pragma unroll
;                 for (int k = 0; k < 8; ++k) { const float g = acc[ai][0][m][k >> 2][k & 3] * rstd, up = acc[ai][1][m][k >> 2][k & 3] * rstd; o[k] = g * sigm(g) * up; }
;                 *(u32x4*)(ACT + (size_t)row * 2816 + u.pn * 128 + wc * 32 + 8 * fq) = pack8_bf16(o);
	v_add_f32_e32 v120, v120, v121
	v_fmamk_f32 v120, v120, 0x3a800000, v195
	v_add_f32_e32 v185, 1.0, v185
	v_add_f32_e32 v187, 1.0, v187
	v_rcp_f32_e32 v198, v185
	v_rcp_f32_e32 v199, v187
	v_rsq_f32_e32 v120, v120
	v_cvt_pk_bf16_f32 v116, v112, v113
	v_mov_b64_e32 v[112:113], s[8:9]
	v_pk_mul_f32 v[126:127], v[126:127], v[198:199]
	v_pk_mul_f32 v[108:109], v[108:109], v[120:121] op_sel_hi:[1,0]
	v_pk_mul_f32 v[118:119], v[118:119], v[126:127]
	v_mul_f32_e32 v121, 0xbfb8aa3b, v108
	v_cvt_pk_bf16_f32 v115, v118, v119
	v_mad_i64_i32 v[118:119], s[24:25], v186, s49, v[112:113]
	v_exp_f32_e32 v121, v121
	v_lshl_add_u64 v[118:119], v[118:119], 0, s[22:23]
	v_lshl_add_u64 v[118:119], v[118:119], 0, s[4:5]
	v_lshl_add_u64 v[118:119], v[118:119], 0, v[160:161]
	global_store_dwordx4 v[118:119], v[114:117], off
	v_pk_mul_f32 v[110:111], v[110:111], v[120:121] op_sel_hi:[1,0]
	v_pk_mul_f32 v[100:101], v[100:101], v[120:121] op_sel_hi:[1,0]
	v_mul_f32_e32 v114, 0xbfb8aa3b, v109
	v_exp_f32_e32 v115, v114
	v_mul_f32_e32 v116, 0xbfb8aa3b, v110
	v_mul_f32_e32 v117, 0xbfb8aa3b, v111
	v_exp_f32_e32 v116, v116
	v_exp_f32_e32 v117, v117
	v_add_f32_e32 v114, 1.0, v121
	v_add_f32_e32 v115, 1.0, v115
	v_rcp_f32_e32 v114, v114
	v_rcp_f32_e32 v115, v115
	v_add_f32_e32 v116, 1.0, v116
	v_add_f32_e32 v117, 1.0, v117
	v_rcp_f32_e32 v116, v116
	v_rcp_f32_e32 v117, v117
	v_pk_mul_f32 v[108:109], v[108:109], v[114:115]
	v_pk_mul_f32 v[102:103], v[102:103], v[120:121] op_sel_hi:[1,0]
	v_pk_mul_f32 v[100:101], v[100:101], v[108:109]
	v_pk_mul_f32 v[108:109], v[110:111], v[116:117]
	v_pk_mul_f32 v[104:105], v[104:105], v[120:121] op_sel_hi:[1,0]
	v_pk_mul_f32 v[102:103], v[102:103], v[108:109]
	v_mul_f32_e32 v110, 0xbfb8aa3b, v104
	v_mul_f32_e32 v108, 0xbfb8aa3b, v105
	v_exp_f32_e32 v110, v110
	v_exp_f32_e32 v109, v108
	v_pk_mul_f32 v[106:107], v[106:107], v[120:121] op_sel_hi:[1,0]
	v_pk_mul_f32 v[96:97], v[96:97], v[120:121] op_sel_hi:[1,0]
	v_add_f32_e32 v108, 1.0, v110
	v_add_f32_e32 v109, 1.0, v109
	v_mul_f32_e32 v110, 0xbfb8aa3b, v106
	v_mul_f32_e32 v111, 0xbfb8aa3b, v107
	v_rcp_f32_e32 v108, v108
	v_rcp_f32_e32 v109, v109
	v_exp_f32_e32 v110, v110
	v_exp_f32_e32 v111, v111
	v_pk_mul_f32 v[104:105], v[104:105], v[108:109]
	v_add_f32_e32 v108, 1.0, v110
	v_add_f32_e32 v109, 1.0, v111
	s_waitcnt vmcnt(6)
	v_mov_b32_e32 v110, v149
	v_mov_b32_e32 v111, v150
	v_mov_b32_e32 v149, v151
	v_pk_add_f32 v[110:111], v[110:111], v[148:149]
	v_rcp_f32_e32 v108, v108
	v_add_f32_e32 v110, v110, v111
	ds_bpermute_b32 v111, v175, v110
	v_rcp_f32_e32 v109, v109
	v_pk_mul_f32 v[104:105], v[96:97], v[104:105]
	v_pk_mul_f32 v[96:97], v[98:99], v[120:121] op_sel_hi:[1,0]
	v_pk_mul_f32 v[98:99], v[106:107], v[108:109]
	s_waitcnt lgkmcnt(0)
	v_add_f32_e32 v108, v110, v111
	ds_bpermute_b32 v109, v173, v108
	v_pk_mul_f32 v[106:107], v[96:97], v[98:99]
	v_cvt_pk_bf16_f32 v96, v100, v101
	v_cvt_pk_bf16_f32 v98, v104, v105
	v_cvt_pk_bf16_f32 v97, v102, v103
	s_waitcnt lgkmcnt(0)
	v_add_f32_e32 v100, v108, v109
	v_fmamk_f32 v100, v100, 0x3a800000, v195
	v_rsq_f32_e32 v100, v100
	v_mad_i64_i32 v[102:103], s[24:25], v184, s49, v[112:113]
	v_lshl_add_u64 v[102:103], v[102:103], 0, s[22:23]
	v_pk_mul_f32 v[92:93], v[92:93], v[100:101] op_sel_hi:[1,0]
	v_lshl_add_u64 v[102:103], v[102:103], 0, s[4:5]
	v_mul_f32_e32 v101, 0xbfb8aa3b, v92
	v_exp_f32_e32 v101, v101
	v_mul_f32_e32 v104, 0xbfb8aa3b, v93
	v_exp_f32_e32 v105, v104
	v_cvt_pk_bf16_f32 v99, v106, v107
	v_add_f32_e32 v101, 1.0, v101
	v_rcp_f32_e32 v104, v101
	v_add_f32_e32 v101, 1.0, v105
	v_rcp_f32_e32 v105, v101
	v_lshl_add_u64 v[102:103], v[102:103], 0, v[160:161]
	v_pk_mul_f32 v[94:95], v[94:95], v[100:101] op_sel_hi:[1,0]
	global_store_dwordx4 v[102:103], v[96:99], off
	v_pk_mul_f32 v[88:89], v[88:89], v[100:101] op_sel_hi:[1,0]
	v_pk_mul_f32 v[92:93], v[92:93], v[104:105]
	v_mul_f32_e32 v96, 0xbfb8aa3b, v94
	v_exp_f32_e32 v96, v96
	v_pk_mul_f32 v[88:89], v[88:89], v[92:93]
	v_mul_f32_e32 v92, 0xbfb8aa3b, v95
	v_exp_f32_e32 v93, v92
	v_pk_mul_f32 v[84:85], v[84:85], v[100:101] op_sel_hi:[1,0]
	v_add_f32_e32 v92, 1.0, v96
	v_mul_f32_e32 v96, 0xbfb8aa3b, v84
	v_mul_f32_e32 v97, 0xbfb8aa3b, v85
	v_exp_f32_e32 v96, v96
	v_exp_f32_e32 v97, v97
	v_add_f32_e32 v93, 1.0, v93
	v_rcp_f32_e32 v92, v92
	v_rcp_f32_e32 v93, v93
	v_add_f32_e32 v96, 1.0, v96
	v_add_f32_e32 v97, 1.0, v97
	v_rcp_f32_e32 v96, v96
	v_rcp_f32_e32 v97, v97
	v_pk_mul_f32 v[90:91], v[90:91], v[100:101] op_sel_hi:[1,0]
	v_pk_mul_f32 v[92:93], v[94:95], v[92:93]
	v_pk_mul_f32 v[86:87], v[86:87], v[100:101] op_sel_hi:[1,0]
	v_pk_mul_f32 v[90:91], v[90:91], v[92:93]
	v_mul_f32_e32 v92, 0xbfb8aa3b, v86
	v_pk_mul_f32 v[80:81], v[80:81], v[100:101] op_sel_hi:[1,0]
	v_pk_mul_f32 v[84:85], v[84:85], v[96:97]
	v_exp_f32_e32 v92, v92
	v_pk_mul_f32 v[84:85], v[80:81], v[84:85]
	v_mul_f32_e32 v80, 0xbfb8aa3b, v87
	v_exp_f32_e32 v81, v80
	v_add_f32_e32 v80, 1.0, v92
	s_waitcnt vmcnt(6)
	v_mov_b32_e32 v92, v145
	v_mov_b32_e32 v93, v146
	v_mov_b32_e32 v145, v147
	v_pk_add_f32 v[92:93], v[92:93], v[144:145]
	v_add_f32_e32 v81, 1.0, v81
	v_add_f32_e32 v92, v92, v93
	v_rcp_f32_e32 v80, v80
	v_rcp_f32_e32 v81, v81
	ds_bpermute_b32 v93, v175, v92
	v_pk_mul_f32 v[82:83], v[82:83], v[100:101] op_sel_hi:[1,0]
	v_pk_mul_f32 v[80:81], v[86:87], v[80:81]
	s_nop 0
	v_pk_mul_f32 v[86:87], v[82:83], v[80:81]
	v_cvt_pk_bf16_f32 v80, v88, v89
	s_waitcnt lgkmcnt(0)
	v_add_f32_e32 v88, v92, v93
	ds_bpermute_b32 v89, v173, v88
	v_cvt_pk_bf16_f32 v83, v86, v87
	v_cvt_pk_bf16_f32 v82, v84, v85
	v_mad_i64_i32 v[84:85], s[24:25], v182, s49, v[112:113]
	s_waitcnt lgkmcnt(0)
; __device__ __forceinline__ float sigm(float x) { return __builtin_amdgcn_rcpf(1.0f + __expf(-x)); }
; __device__ __forceinline__ u32x4 pack8_bf16(const float (&o)[8]) { u32x4 w; w.x = cvt_pk_bf16(o[0], o[1]); w.y = cvt_pk_bf16(o[2], o[3]); w.z = cvt_pk_bf16(o[4], o[5]); w.w = cvt_pk_bf16(o[6], o[7]); return w; }
;     __device__ __forceinline__ void operator()(const f32x4 (&acc)[2][2][4][2], const Unit& u, int wr, int wc, int fr, int fq) const {
;     ...
;         for (int ai = 0; ai < 2; ++ai)
; #pragma unroll
;             for (int m = 0; m < 4; ++m) {
;                 const int row = row0 + ai * HALF + m * 16;
;                 float ss = (sq[ai][m][0] + sq[ai][m][1]) + (sq[ai][m][2] + sq[ai][m][3]);
;                 ss += __shfl_xor(ss, 16); ss += __shfl_xor(ss, 32);
;                 const float rstd = __builtin_amdgcn_rsqf(ss * (1.0f / 1024.0f) + 1e-6f);
;                 float o[8];
; #pragma unroll
;                 for (int k = 0; k < 8; ++k) { const float g = acc[ai][0][m][k >> 2][k & 3] * rstd, up = acc[ai][1][m][k >> 2][k & 3] * rstd; o[k] = g * sigm(g) * up; }
;                 *(u32x4*)(ACT + (size_t)row * 2816 + u.pn * 128 + wc * 32 + 8 * fq) = pack8_bf16(o);
	v_add_f32_e32 v86, v88, v89
	v_fmamk_f32 v86, v86, 0x3a800000, v195
	v_rsq_f32_e32 v86, v86
	v_lshl_add_u64 v[84:85], v[84:85], 0, s[22:23]
	v_lshl_add_u64 v[84:85], v[84:85], 0, s[4:5]
	v_cvt_pk_bf16_f32 v81, v90, v91
	v_pk_mul_f32 v[76:77], v[76:77], v[86:87] op_sel_hi:[1,0]
	v_lshl_add_u64 v[84:85], v[84:85], 0, v[160:161]
	v_mul_f32_e32 v87, 0xbfb8aa3b, v76
	v_exp_f32_e32 v87, v87
	global_store_dwordx4 v[84:85], v[80:83], off
	v_pk_mul_f32 v[78:79], v[78:79], v[86:87] op_sel_hi:[1,0]
	s_nop 0
	v_mul_f32_e32 v80, 0xbfb8aa3b, v77
	v_exp_f32_e32 v81, v80
	v_mul_f32_e32 v82, 0xbfb8aa3b, v78
	v_mul_f32_e32 v83, 0xbfb8aa3b, v79
	v_exp_f32_e32 v82, v82
	v_exp_f32_e32 v83, v83
	v_add_f32_e32 v80, 1.0, v87
	v_add_f32_e32 v81, 1.0, v81
	v_rcp_f32_e32 v80, v80
	v_rcp_f32_e32 v81, v81
	v_add_f32_e32 v82, 1.0, v82
	v_add_f32_e32 v83, 1.0, v83
	v_rcp_f32_e32 v82, v82
	v_rcp_f32_e32 v83, v83
	v_pk_mul_f32 v[68:69], v[68:69], v[86:87] op_sel_hi:[1,0]
	v_pk_mul_f32 v[76:77], v[76:77], v[80:81]
	v_pk_mul_f32 v[70:71], v[70:71], v[86:87] op_sel_hi:[1,0]
	v_pk_mul_f32 v[68:69], v[68:69], v[76:77]
	v_pk_mul_f32 v[76:77], v[78:79], v[82:83]
	v_pk_mul_f32 v[72:73], v[72:73], v[86:87] op_sel_hi:[1,0]
	v_pk_mul_f32 v[70:71], v[70:71], v[76:77]
	v_mul_f32_e32 v78, 0xbfb8aa3b, v72
	v_mul_f32_e32 v76, 0xbfb8aa3b, v73
	v_exp_f32_e32 v78, v78
	v_exp_f32_e32 v77, v76
	v_pk_mul_f32 v[74:75], v[74:75], v[86:87] op_sel_hi:[1,0]
	v_pk_mul_f32 v[64:65], v[64:65], v[86:87] op_sel_hi:[1,0]
	v_add_f32_e32 v76, 1.0, v78
	v_add_f32_e32 v77, 1.0, v77
	v_mul_f32_e32 v78, 0xbfb8aa3b, v74
	v_mul_f32_e32 v79, 0xbfb8aa3b, v75
	v_rcp_f32_e32 v76, v76
	v_rcp_f32_e32 v77, v77
	v_exp_f32_e32 v78, v78
	v_exp_f32_e32 v79, v79
	v_pk_mul_f32 v[72:73], v[72:73], v[76:77]
	v_add_f32_e32 v76, 1.0, v78
	v_add_f32_e32 v77, 1.0, v79
	s_waitcnt vmcnt(6)
	v_mov_b32_e32 v78, v141
	v_mov_b32_e32 v79, v142
	v_mov_b32_e32 v141, v143
	v_pk_add_f32 v[78:79], v[78:79], v[140:141]
	v_rcp_f32_e32 v76, v76
	v_add_f32_e32 v78, v78, v79
	ds_bpermute_b32 v79, v175, v78
	v_rcp_f32_e32 v77, v77
	v_pk_mul_f32 v[72:73], v[64:65], v[72:73]
	v_pk_mul_f32 v[64:65], v[66:67], v[86:87] op_sel_hi:[1,0]
	v_pk_mul_f32 v[66:67], v[74:75], v[76:77]
	s_waitcnt lgkmcnt(0)
	v_add_f32_e32 v76, v78, v79
	ds_bpermute_b32 v77, v173, v76
	v_pk_mul_f32 v[74:75], v[64:65], v[66:67]
	v_cvt_pk_bf16_f32 v64, v68, v69
	v_cvt_pk_bf16_f32 v66, v72, v73
	v_cvt_pk_bf16_f32 v65, v70, v71
	s_waitcnt lgkmcnt(0)
	v_add_f32_e32 v68, v76, v77
	v_fmamk_f32 v68, v68, 0x3a800000, v195
	v_rsq_f32_e32 v68, v68
	v_mad_i64_i32 v[70:71], s[24:25], v180, s49, v[112:113]
	v_lshl_add_u64 v[70:71], v[70:71], 0, s[22:23]
	v_pk_mul_f32 v[60:61], v[60:61], v[68:69] op_sel_hi:[1,0]
	v_lshl_add_u64 v[70:71], v[70:71], 0, s[4:5]
	v_mul_f32_e32 v69, 0xbfb8aa3b, v60
	v_exp_f32_e32 v69, v69
	v_mul_f32_e32 v72, 0xbfb8aa3b, v61
	v_exp_f32_e32 v73, v72
	v_cvt_pk_bf16_f32 v67, v74, v75
	v_add_f32_e32 v69, 1.0, v69
	v_rcp_f32_e32 v72, v69
	v_add_f32_e32 v69, 1.0, v73
	v_rcp_f32_e32 v73, v69
	v_lshl_add_u64 v[70:71], v[70:71], 0, v[160:161]
	v_pk_mul_f32 v[62:63], v[62:63], v[68:69] op_sel_hi:[1,0]
	global_store_dwordx4 v[70:71], v[64:67], off
	s_cmp_eq_u32 s50, 6
	s_cbranch_scc1 .Lp5_epi_end
	v_pk_mul_f32 v[56:57], v[56:57], v[68:69] op_sel_hi:[1,0]
	v_pk_mul_f32 v[60:61], v[60:61], v[72:73]
	v_mul_f32_e32 v64, 0xbfb8aa3b, v62
	v_exp_f32_e32 v64, v64
	v_pk_mul_f32 v[56:57], v[56:57], v[60:61]
	v_mul_f32_e32 v60, 0xbfb8aa3b, v63
	v_exp_f32_e32 v61, v60
	v_pk_mul_f32 v[52:53], v[52:53], v[68:69] op_sel_hi:[1,0]
	v_add_f32_e32 v60, 1.0, v64
	v_mul_f32_e32 v64, 0xbfb8aa3b, v52
	v_mul_f32_e32 v65, 0xbfb8aa3b, v53
	v_exp_f32_e32 v64, v64
	v_exp_f32_e32 v65, v65
	v_add_f32_e32 v61, 1.0, v61
	v_rcp_f32_e32 v60, v60
	v_rcp_f32_e32 v61, v61
	v_add_f32_e32 v64, 1.0, v64
	v_add_f32_e32 v65, 1.0, v65
	v_rcp_f32_e32 v64, v64
	v_rcp_f32_e32 v65, v65
	v_pk_mul_f32 v[58:59], v[58:59], v[68:69] op_sel_hi:[1,0]
	v_pk_mul_f32 v[60:61], v[62:63], v[60:61]
	v_pk_mul_f32 v[54:55], v[54:55], v[68:69] op_sel_hi:[1,0]
	v_pk_mul_f32 v[58:59], v[58:59], v[60:61]
	v_mul_f32_e32 v60, 0xbfb8aa3b, v54
	v_pk_mul_f32 v[48:49], v[48:49], v[68:69] op_sel_hi:[1,0]
	v_pk_mul_f32 v[52:53], v[52:53], v[64:65]
	v_exp_f32_e32 v60, v60
	v_pk_mul_f32 v[52:53], v[48:49], v[52:53]
	v_mul_f32_e32 v48, 0xbfb8aa3b, v55
	v_exp_f32_e32 v49, v48
	v_add_f32_e32 v48, 1.0, v60
	s_waitcnt vmcnt(6)
	v_mov_b32_e32 v60, v137
	v_mov_b32_e32 v61, v138
	v_mov_b32_e32 v137, v139
	v_pk_add_f32 v[60:61], v[60:61], v[136:137]
	v_add_f32_e32 v49, 1.0, v49
	v_add_f32_e32 v60, v60, v61
	v_rcp_f32_e32 v48, v48
	v_rcp_f32_e32 v49, v49
	ds_bpermute_b32 v61, v175, v60
	v_pk_mul_f32 v[50:51], v[50:51], v[68:69] op_sel_hi:[1,0]
	v_pk_mul_f32 v[48:49], v[54:55], v[48:49]
	s_nop 0
	v_pk_mul_f32 v[54:55], v[50:51], v[48:49]
	v_cvt_pk_bf16_f32 v48, v56, v57
	s_waitcnt lgkmcnt(0)
	v_add_f32_e32 v56, v60, v61
	ds_bpermute_b32 v57, v173, v56
	v_cvt_pk_bf16_f32 v51, v54, v55
	v_cvt_pk_bf16_f32 v50, v52, v53
	v_mad_i64_i32 v[52:53], s[24:25], v178, s49, v[112:113]
	s_waitcnt lgkmcnt(0)
; __device__ __forceinline__ float sigm(float x) { return __builtin_amdgcn_rcpf(1.0f + __expf(-x)); }
; __device__ __forceinline__ u32x4 pack8_bf16(const float (&o)[8]) { u32x4 w; w.x = cvt_pk_bf16(o[0], o[1]); w.y = cvt_pk_bf16(o[2], o[3]); w.z = cvt_pk_bf16(o[4], o[5]); w.w = cvt_pk_bf16(o[6], o[7]); return w; }
;     __device__ __forceinline__ void operator()(const f32x4 (&acc)[2][2][4][2], const Unit& u, int wr, int wc, int fr, int fq) const {
;     ...
;         for (int ai = 0; ai < 2; ++ai)
; #pragma unroll
;             for (int m = 0; m < 4; ++m) {
;                 const int row = row0 + ai * HALF + m * 16;
;                 float ss = (sq[ai][m][0] + sq[ai][m][1]) + (sq[ai][m][2] + sq[ai][m][3]);
;                 ss += __shfl_xor(ss, 16); ss += __shfl_xor(ss, 32);
;                 const float rstd = __builtin_amdgcn_rsqf(ss * (1.0f / 1024.0f) + 1e-6f);
;                 float o[8];
; #pragma unroll
;                 for (int k = 0; k < 8; ++k) { const float g = acc[ai][0][m][k >> 2][k & 3] * rstd, up = acc[ai][1][m][k >> 2][k & 3] * rstd; o[k] = g * sigm(g) * up; }
;                 *(u32x4*)(ACT + (size_t)row * 2816 + u.pn * 128 + wc * 32 + 8 * fq) = pack8_bf16(o);
	v_add_f32_e32 v54, v56, v57
	v_fmamk_f32 v54, v54, 0x3a800000, v195
	v_rsq_f32_e32 v54, v54
	v_lshl_add_u64 v[52:53], v[52:53], 0, s[22:23]
	v_lshl_add_u64 v[52:53], v[52:53], 0, s[4:5]
	v_cvt_pk_bf16_f32 v49, v58, v59
	v_pk_mul_f32 v[44:45], v[44:45], v[54:55] op_sel_hi:[1,0]
	v_lshl_add_u64 v[52:53], v[52:53], 0, v[160:161]
	v_mul_f32_e32 v55, 0xbfb8aa3b, v44
	v_exp_f32_e32 v55, v55
	global_store_dwordx4 v[52:53], v[48:51], off
	v_pk_mul_f32 v[46:47], v[46:47], v[54:55] op_sel_hi:[1,0]
	s_nop 0
	v_mul_f32_e32 v48, 0xbfb8aa3b, v45
	v_exp_f32_e32 v49, v48
	v_mul_f32_e32 v50, 0xbfb8aa3b, v46
	v_mul_f32_e32 v51, 0xbfb8aa3b, v47
	v_exp_f32_e32 v50, v50
	v_exp_f32_e32 v51, v51
	v_add_f32_e32 v48, 1.0, v55
	v_add_f32_e32 v49, 1.0, v49
	v_rcp_f32_e32 v48, v48
	v_rcp_f32_e32 v49, v49
	v_add_f32_e32 v50, 1.0, v50
	v_add_f32_e32 v51, 1.0, v51
	v_rcp_f32_e32 v50, v50
	v_rcp_f32_e32 v51, v51
	v_pk_mul_f32 v[36:37], v[36:37], v[54:55] op_sel_hi:[1,0]
	v_pk_mul_f32 v[44:45], v[44:45], v[48:49]
	v_pk_mul_f32 v[38:39], v[38:39], v[54:55] op_sel_hi:[1,0]
	v_pk_mul_f32 v[36:37], v[36:37], v[44:45]
	v_pk_mul_f32 v[44:45], v[46:47], v[50:51]
	v_pk_mul_f32 v[40:41], v[40:41], v[54:55] op_sel_hi:[1,0]
	v_pk_mul_f32 v[38:39], v[38:39], v[44:45]
	v_mul_f32_e32 v46, 0xbfb8aa3b, v40
	v_mul_f32_e32 v44, 0xbfb8aa3b, v41
	v_exp_f32_e32 v46, v46
	v_exp_f32_e32 v45, v44
	v_pk_mul_f32 v[42:43], v[42:43], v[54:55] op_sel_hi:[1,0]
	v_pk_mul_f32 v[32:33], v[32:33], v[54:55] op_sel_hi:[1,0]
	v_add_f32_e32 v44, 1.0, v46
	v_add_f32_e32 v45, 1.0, v45
	v_mul_f32_e32 v46, 0xbfb8aa3b, v42
	v_mul_f32_e32 v47, 0xbfb8aa3b, v43
	v_rcp_f32_e32 v44, v44
	v_rcp_f32_e32 v45, v45
	v_exp_f32_e32 v46, v46
	v_exp_f32_e32 v47, v47
	v_pk_mul_f32 v[40:41], v[40:41], v[44:45]
	v_add_f32_e32 v44, 1.0, v46
	v_add_f32_e32 v45, 1.0, v47
	s_waitcnt vmcnt(6)
	v_mov_b32_e32 v46, v133
	v_mov_b32_e32 v47, v134
	v_mov_b32_e32 v133, v135
	v_pk_add_f32 v[46:47], v[46:47], v[132:133]
	v_rcp_f32_e32 v44, v44
	v_add_f32_e32 v46, v46, v47
	ds_bpermute_b32 v47, v175, v46
	v_rcp_f32_e32 v45, v45
	v_pk_mul_f32 v[40:41], v[32:33], v[40:41]
	v_pk_mul_f32 v[32:33], v[34:35], v[54:55] op_sel_hi:[1,0]
	v_pk_mul_f32 v[34:35], v[42:43], v[44:45]
	s_waitcnt lgkmcnt(0)
	v_add_f32_e32 v44, v46, v47
	ds_bpermute_b32 v45, v173, v44
	v_pk_mul_f32 v[42:43], v[32:33], v[34:35]
	v_cvt_pk_bf16_f32 v32, v36, v37
	v_cvt_pk_bf16_f32 v34, v40, v41
	v_cvt_pk_bf16_f32 v33, v38, v39
	s_waitcnt lgkmcnt(0)
	v_add_f32_e32 v36, v44, v45
	v_fmamk_f32 v36, v36, 0x3a800000, v195
	v_rsq_f32_e32 v36, v36
	v_mad_i64_i32 v[38:39], s[24:25], v176, s49, v[112:113]
	v_lshl_add_u64 v[38:39], v[38:39], 0, s[22:23]
	v_pk_mul_f32 v[28:29], v[28:29], v[36:37] op_sel_hi:[1,0]
	v_lshl_add_u64 v[38:39], v[38:39], 0, s[4:5]
	v_mul_f32_e32 v37, 0xbfb8aa3b, v28
	v_exp_f32_e32 v37, v37
	v_mul_f32_e32 v40, 0xbfb8aa3b, v29
	v_exp_f32_e32 v41, v40
	v_cvt_pk_bf16_f32 v35, v42, v43
	v_add_f32_e32 v37, 1.0, v37
	v_rcp_f32_e32 v40, v37
	v_add_f32_e32 v37, 1.0, v41
	v_rcp_f32_e32 v41, v37
	v_lshl_add_u64 v[38:39], v[38:39], 0, v[160:161]
	v_pk_mul_f32 v[30:31], v[30:31], v[36:37] op_sel_hi:[1,0]
	global_store_dwordx4 v[38:39], v[32:35], off
	v_pk_mul_f32 v[24:25], v[24:25], v[36:37] op_sel_hi:[1,0]
	v_pk_mul_f32 v[28:29], v[28:29], v[40:41]
	v_mul_f32_e32 v32, 0xbfb8aa3b, v30
	v_exp_f32_e32 v32, v32
	v_pk_mul_f32 v[24:25], v[24:25], v[28:29]
	v_mul_f32_e32 v28, 0xbfb8aa3b, v31
	v_exp_f32_e32 v29, v28
	v_pk_mul_f32 v[20:21], v[20:21], v[36:37] op_sel_hi:[1,0]
	v_add_f32_e32 v28, 1.0, v32
	v_mul_f32_e32 v32, 0xbfb8aa3b, v20
	v_mul_f32_e32 v33, 0xbfb8aa3b, v21
	v_exp_f32_e32 v32, v32
	v_exp_f32_e32 v33, v33
	v_add_f32_e32 v29, 1.0, v29
	v_rcp_f32_e32 v28, v28
	v_rcp_f32_e32 v29, v29
	v_add_f32_e32 v32, 1.0, v32
	v_add_f32_e32 v33, 1.0, v33
	v_rcp_f32_e32 v32, v32
	v_rcp_f32_e32 v33, v33
	v_pk_mul_f32 v[26:27], v[26:27], v[36:37] op_sel_hi:[1,0]
	v_pk_mul_f32 v[28:29], v[30:31], v[28:29]
	v_pk_mul_f32 v[22:23], v[22:23], v[36:37] op_sel_hi:[1,0]
	v_pk_mul_f32 v[26:27], v[26:27], v[28:29]
	v_mul_f32_e32 v28, 0xbfb8aa3b, v22
	v_pk_mul_f32 v[16:17], v[16:17], v[36:37] op_sel_hi:[1,0]
	v_pk_mul_f32 v[20:21], v[20:21], v[32:33]
	v_exp_f32_e32 v28, v28
	v_pk_mul_f32 v[20:21], v[16:17], v[20:21]
	v_mul_f32_e32 v16, 0xbfb8aa3b, v23
	v_exp_f32_e32 v17, v16
	v_add_f32_e32 v16, 1.0, v28
	s_waitcnt vmcnt(6)
; __device__ __forceinline__ float sigm(float x) { return __builtin_amdgcn_rcpf(1.0f + __expf(-x)); }
; __device__ __forceinline__ u32x4 pack8_bf16(const float (&o)[8]) { u32x4 w; w.x = cvt_pk_bf16(o[0], o[1]); w.y = cvt_pk_bf16(o[2], o[3]); w.z = cvt_pk_bf16(o[4], o[5]); w.w = cvt_pk_bf16(o[6], o[7]); return w; }
;     __device__ __forceinline__ void operator()(const f32x4 (&acc)[2][2][4][2], const Unit& u, int wr, int wc, int fr, int fq) const {
;     ...
;         for (int ai = 0; ai < 2; ++ai)
; #pragma unroll
;             for (int m = 0; m < 4; ++m) {
;                 const int row = row0 + ai * HALF + m * 16;
;                 float ss = (sq[ai][m][0] + sq[ai][m][1]) + (sq[ai][m][2] + sq[ai][m][3]);
;                 ss += __shfl_xor(ss, 16); ss += __shfl_xor(ss, 32);
;                 const float rstd = __builtin_amdgcn_rsqf(ss * (1.0f / 1024.0f) + 1e-6f);
;                 float o[8];
; #pragma unroll
;                 for (int k = 0; k < 8; ++k) { const float g = acc[ai][0][m][k >> 2][k & 3] * rstd, up = acc[ai][1][m][k >> 2][k & 3] * rstd; o[k] = g * sigm(g) * up; }
;                 *(u32x4*)(ACT + (size_t)row * 2816 + u.pn * 128 + wc * 32 + 8 * fq) = pack8_bf16(o);
	v_mov_b32_e32 v28, v129
	v_mov_b32_e32 v29, v130
	v_mov_b32_e32 v129, v131
	v_pk_add_f32 v[28:29], v[28:29], v[128:129]
	v_add_f32_e32 v17, 1.0, v17
	v_add_f32_e32 v28, v28, v29
	v_rcp_f32_e32 v16, v16
	v_rcp_f32_e32 v17, v17
	ds_bpermute_b32 v29, v175, v28
	v_pk_mul_f32 v[18:19], v[18:19], v[36:37] op_sel_hi:[1,0]
	v_pk_mul_f32 v[16:17], v[22:23], v[16:17]
	s_nop 0
	v_pk_mul_f32 v[22:23], v[18:19], v[16:17]
	v_cvt_pk_bf16_f32 v16, v24, v25
	s_waitcnt lgkmcnt(0)
	v_add_f32_e32 v24, v28, v29
	ds_bpermute_b32 v25, v173, v24
	v_cvt_pk_bf16_f32 v19, v22, v23
	v_cvt_pk_bf16_f32 v18, v20, v21
	v_mad_i64_i32 v[20:21], s[24:25], v174, s49, v[112:113]
	s_waitcnt lgkmcnt(0)
	v_add_f32_e32 v22, v24, v25
	v_fmamk_f32 v22, v22, 0x3a800000, v195
	v_rsq_f32_e32 v22, v22
	v_lshl_add_u64 v[20:21], v[20:21], 0, s[22:23]
	v_lshl_add_u64 v[20:21], v[20:21], 0, s[4:5]
	v_cvt_pk_bf16_f32 v17, v26, v27
	v_pk_mul_f32 v[12:13], v[12:13], v[22:23] op_sel_hi:[1,0]
	v_lshl_add_u64 v[20:21], v[20:21], 0, v[160:161]
	v_mul_f32_e32 v23, 0xbfb8aa3b, v12
	v_exp_f32_e32 v23, v23
	global_store_dwordx4 v[20:21], v[16:19], off
	v_pk_mul_f32 v[14:15], v[14:15], v[22:23] op_sel_hi:[1,0]
	s_nop 0
	v_mul_f32_e32 v16, 0xbfb8aa3b, v13
	v_exp_f32_e32 v17, v16
	v_mul_f32_e32 v18, 0xbfb8aa3b, v14
	v_mul_f32_e32 v19, 0xbfb8aa3b, v15
	v_exp_f32_e32 v18, v18
	v_exp_f32_e32 v19, v19
	v_add_f32_e32 v16, 1.0, v23
	v_add_f32_e32 v17, 1.0, v17
	v_rcp_f32_e32 v16, v16
	v_rcp_f32_e32 v17, v17
	v_add_f32_e32 v18, 1.0, v18
	v_add_f32_e32 v19, 1.0, v19
	v_rcp_f32_e32 v18, v18
	v_rcp_f32_e32 v19, v19
	v_pk_mul_f32 v[4:5], v[4:5], v[22:23] op_sel_hi:[1,0]
	v_pk_mul_f32 v[12:13], v[12:13], v[16:17]
	v_pk_mul_f32 v[8:9], v[8:9], v[22:23] op_sel_hi:[1,0]
	v_pk_mul_f32 v[4:5], v[4:5], v[12:13]
	v_pk_mul_f32 v[12:13], v[14:15], v[18:19]
	v_mul_f32_e32 v14, 0xbfb8aa3b, v8
	v_exp_f32_e32 v14, v14
	v_pk_mul_f32 v[6:7], v[6:7], v[22:23] op_sel_hi:[1,0]
	v_pk_mul_f32 v[10:11], v[10:11], v[22:23] op_sel_hi:[1,0]
	v_pk_mul_f32 v[6:7], v[6:7], v[12:13]
	v_mul_f32_e32 v12, 0xbfb8aa3b, v9
	v_exp_f32_e32 v13, v12
	v_add_f32_e32 v12, 1.0, v14
	v_mul_f32_e32 v14, 0xbfb8aa3b, v10
	v_mul_f32_e32 v15, 0xbfb8aa3b, v11
	v_exp_f32_e32 v14, v14
	v_exp_f32_e32 v15, v15
	v_add_f32_e32 v13, 1.0, v13
	v_rcp_f32_e32 v12, v12
	v_rcp_f32_e32 v13, v13
	v_add_f32_e32 v14, 1.0, v14
	v_add_f32_e32 v15, 1.0, v15
	v_rcp_f32_e32 v14, v14
	v_rcp_f32_e32 v15, v15
	v_pk_mul_f32 v[0:1], v[0:1], v[22:23] op_sel_hi:[1,0]
	v_pk_mul_f32 v[8:9], v[8:9], v[12:13]
	s_nop 0
	v_pk_mul_f32 v[8:9], v[0:1], v[8:9]
	v_pk_mul_f32 v[0:1], v[2:3], v[22:23] op_sel_hi:[1,0]
	v_pk_mul_f32 v[2:3], v[10:11], v[14:15]
	s_nop 0
	v_pk_mul_f32 v[10:11], v[0:1], v[2:3]
	v_cvt_pk_bf16_f32 v0, v4, v5
	v_mad_i64_i32 v[4:5], s[24:25], v172, s49, v[112:113]
	v_lshl_add_u64 v[4:5], v[4:5], 0, s[22:23]
	v_lshl_add_u64 v[4:5], v[4:5], 0, s[4:5]
	v_cvt_pk_bf16_f32 v1, v6, v7
	v_cvt_pk_bf16_f32 v2, v8, v9
	v_cvt_pk_bf16_f32 v3, v10, v11
	v_lshl_add_u64 v[4:5], v[4:5], 0, v[160:161]
	global_store_dwordx4 v[4:5], v[0:3], off
.Lp5_epi_end:
	s_cbranch_vccnz .LBB0_965
	s_andn2_b64 vcc, exec, s[6:7]
	s_cbranch_vccnz .LBB0_964
	s_barrier
	s_branch .LBB0_964
